# cross-attention units remapped so batch == blockIdx%8 (XCD-local like the GEMM rows); XQ->xattn and xattn->XO syncs (17,18) now XCD-local too (guarded), on top of local syncs 4,8,9,10,20
# speedup vs baseline: 1.0134x; 1.0057x over previous
; __device__ __forceinline__ float bf2f(unsigned h) { return __uint_as_float(h << 16); }
; template <int DQK, int DV, int MODE, bool QNORM, int SK, int NQ> ...
;     ...
;     bf16x8 qf[NQ][DQK / 16];
; #pragma unroll
;     for (int qh = 0; qh < NQ; ++qh)
; #pragma unroll
;         for (int d0 = 0; d0 < DQK / 16; ++d0) qf[qh][d0] = *(const bf16x8*)(Qp + (size_t)qh * q_hoff + (size_t)r32 * q_pitch + d0 * 16 + hi * 8);
;     float sscale[NQ];
; #pragma unroll
;     for (int qh = 0; qh < NQ; ++qh) {
;         sscale[qh] = 1.0f;
;         if (QNORM) {
;             float ss = 0.f;
; #pragma unroll
;             for (int d0 = 0; d0 < DQK / 16; ++d0)
; #pragma unroll
;                 for (int jq = 0; jq < 8; ++jq) { const float v = bf2f((unsigned)(unsigned short)qf[qh][d0][jq]); ss += v * v; }
;             ss += __shfl_xor(ss, 32);
;             sscale[qh] = qk_scale * __builtin_amdgcn_rsqf(ss * (1.0f / DQK) + EPS);
; __global__ void __launch_bounds__(512, 2) mega_fwd(KArgs a) {
;     ...
;         for (int ub = blockIdx.x; ub < 512; ub += GRID_BLOCKS) {
;             const int half = ub & 1, h = (ub >> 1) & 3, qblk = ub >> 3, b = qblk >> 3;
;             const int tok0 = qblk * 256 + wave * 32;
;             f32x16 o[1][4]; float mm[1], ll[1];
;             const size_t kvb = (size_t)((l * 8 + b) * 4 + h) * 256;
;             attn_block<256, 128, 2, true, 32, 1>(lds, RA + (size_t)tok0 * 1024 + h * 256, 1024, 0, KX + kvb * 256, 256, VTX + (kvb + half * 128) * 256, 256,
.LBB0_4642:
	s_and_b32 s30, s26, 7
	s_lshl_b32 s30, s30, 6
	s_lshr_b32 s31, s26, 3
	s_or_b32 s30, s30, s31
	s_lshl_b32 s2, s30, 5
	s_ashr_i32 s3, s30, 4
	s_and_b32 s2, s2, 0xffffff00
	s_and_b32 s3, s3, -4
	s_bfe_u32 s27, s30, 0x20001
	s_add_i32 s2, s2, s18
	s_add_i32 s3, s3, s19
	s_or_b32 s12, s3, s27
	s_ashr_i32 s3, s2, 31
	s_ashr_i32 s13, s12, 31
	s_lshl_b64 s[14:15], s[2:3], 11
	s_add_u32 s3, s20, s14
	s_addc_u32 s14, s21, s15
	s_lshl_b32 s15, s27, 9
	s_add_u32 s16, s3, s15
	s_addc_u32 s17, s14, 0
	v_mov_b32_e32 v165, v0
	v_lshl_add_u64 v[2:3], s[16:17], 0, v[164:165]
	v_mov_b32_e32 v167, v0
	v_lshl_add_u64 v[2:3], v[2:3], 0, v[166:167]
	global_load_dwordx4 v[142:145], v[2:3], off
	global_load_dwordx4 v[138:141], v[2:3], off offset:32
	global_load_dwordx4 v[134:137], v[2:3], off offset:64
	global_load_dwordx4 v[126:129], v[2:3], off offset:96
	global_load_dwordx4 v[118:121], v[2:3], off offset:128
	global_load_dwordx4 v[110:113], v[2:3], off offset:160
	global_load_dwordx4 v[102:105], v[2:3], off offset:192
	global_load_dwordx4 v[130:133], v[2:3], off offset:224
	global_load_dwordx4 v[122:125], v[2:3], off offset:256
	global_load_dwordx4 v[114:117], v[2:3], off offset:288
	global_load_dwordx4 v[106:109], v[2:3], off offset:320
	global_load_dwordx4 v[98:101], v[2:3], off offset:352
	global_load_dwordx4 v[94:97], v[2:3], off offset:384
	global_load_dwordx4 v[90:93], v[2:3], off offset:416
	global_load_dwordx4 v[86:89], v[2:3], off offset:448
	global_load_dwordx4 v[82:85], v[2:3], off offset:480
	s_lshl_b64 s[14:15], s[12:13], 17
	s_add_u32 s12, s22, s14
	s_addc_u32 s13, s23, s15
	s_lshl_b32 s3, s30, 7
	s_and_b32 s3, s3, 0x80
	s_add_u32 s14, s24, s14
	s_addc_u32 s15, s25, s15
	s_lshl_b32 s28, s3, 9
	s_add_u32 s14, s14, s28
	s_addc_u32 s15, s15, 0
	s_waitcnt vmcnt(15)
	v_and_b32_e32 v1, 0xffff0000, v142
	v_lshlrev_b32_e32 v2, 16, v142
	v_mul_f32_e32 v1, v1, v1
	v_fmac_f32_e32 v1, v2, v2
	v_lshlrev_b32_e32 v2, 16, v143
	v_fmac_f32_e32 v1, v2, v2
	v_and_b32_e32 v2, 0xffff0000, v143
	v_fmac_f32_e32 v1, v2, v2
	v_lshlrev_b32_e32 v2, 16, v144
	v_fmac_f32_e32 v1, v2, v2
	v_and_b32_e32 v2, 0xffff0000, v144
	v_fmac_f32_e32 v1, v2, v2
	v_lshlrev_b32_e32 v2, 16, v145
	v_fmac_f32_e32 v1, v2, v2
	v_and_b32_e32 v2, 0xffff0000, v145
	v_fmac_f32_e32 v1, v2, v2
	s_waitcnt vmcnt(14)
	v_lshlrev_b32_e32 v2, 16, v138
	v_fmac_f32_e32 v1, v2, v2
	v_and_b32_e32 v2, 0xffff0000, v138
	v_fmac_f32_e32 v1, v2, v2
	v_lshlrev_b32_e32 v2, 16, v139
	v_fmac_f32_e32 v1, v2, v2
	v_and_b32_e32 v2, 0xffff0000, v139
	v_fmac_f32_e32 v1, v2, v2
	v_lshlrev_b32_e32 v2, 16, v140
	v_fmac_f32_e32 v1, v2, v2
	v_and_b32_e32 v2, 0xffff0000, v140
	v_fmac_f32_e32 v1, v2, v2
	v_lshlrev_b32_e32 v2, 16, v141
	v_fmac_f32_e32 v1, v2, v2
	v_and_b32_e32 v2, 0xffff0000, v141
	v_fmac_f32_e32 v1, v2, v2
	s_waitcnt vmcnt(13)
	v_lshlrev_b32_e32 v2, 16, v134
	v_fmac_f32_e32 v1, v2, v2
	v_and_b32_e32 v2, 0xffff0000, v134
	v_fmac_f32_e32 v1, v2, v2
	v_lshlrev_b32_e32 v2, 16, v135
	v_fmac_f32_e32 v1, v2, v2
	v_and_b32_e32 v2, 0xffff0000, v135
	v_fmac_f32_e32 v1, v2, v2
	v_lshlrev_b32_e32 v2, 16, v136
	v_fmac_f32_e32 v1, v2, v2
	v_and_b32_e32 v2, 0xffff0000, v136
	v_fmac_f32_e32 v1, v2, v2
	v_lshlrev_b32_e32 v2, 16, v137
	v_fmac_f32_e32 v1, v2, v2
	v_and_b32_e32 v2, 0xffff0000, v137
	v_fmac_f32_e32 v1, v2, v2
	s_waitcnt vmcnt(12)
	v_lshlrev_b32_e32 v2, 16, v126
	v_fmac_f32_e32 v1, v2, v2
	v_and_b32_e32 v2, 0xffff0000, v126
	v_fmac_f32_e32 v1, v2, v2
	v_lshlrev_b32_e32 v2, 16, v127
	v_fmac_f32_e32 v1, v2, v2
	v_and_b32_e32 v2, 0xffff0000, v127
	v_fmac_f32_e32 v1, v2, v2
	v_lshlrev_b32_e32 v2, 16, v128
	v_fmac_f32_e32 v1, v2, v2
	v_and_b32_e32 v2, 0xffff0000, v128
	v_fmac_f32_e32 v1, v2, v2
	v_lshlrev_b32_e32 v2, 16, v129
	v_fmac_f32_e32 v1, v2, v2
	v_and_b32_e32 v2, 0xffff0000, v129
	v_fmac_f32_e32 v1, v2, v2
	s_waitcnt vmcnt(11)
	v_lshlrev_b32_e32 v2, 16, v118
	v_fmac_f32_e32 v1, v2, v2
	v_and_b32_e32 v2, 0xffff0000, v118
	v_fmac_f32_e32 v1, v2, v2
	v_lshlrev_b32_e32 v2, 16, v119
	v_fmac_f32_e32 v1, v2, v2
	v_and_b32_e32 v2, 0xffff0000, v119
	v_fmac_f32_e32 v1, v2, v2
	v_lshlrev_b32_e32 v2, 16, v120
	v_fmac_f32_e32 v1, v2, v2
	v_and_b32_e32 v2, 0xffff0000, v120
	v_fmac_f32_e32 v1, v2, v2
	v_lshlrev_b32_e32 v2, 16, v121
	v_fmac_f32_e32 v1, v2, v2
	v_and_b32_e32 v2, 0xffff0000, v121
	v_fmac_f32_e32 v1, v2, v2
	s_waitcnt vmcnt(10)
	v_lshlrev_b32_e32 v2, 16, v110
	v_fmac_f32_e32 v1, v2, v2
	v_and_b32_e32 v2, 0xffff0000, v110
	v_fmac_f32_e32 v1, v2, v2
	v_lshlrev_b32_e32 v2, 16, v111
	v_fmac_f32_e32 v1, v2, v2
	v_and_b32_e32 v2, 0xffff0000, v111
	v_fmac_f32_e32 v1, v2, v2
	v_lshlrev_b32_e32 v2, 16, v112
	v_fmac_f32_e32 v1, v2, v2
	v_and_b32_e32 v2, 0xffff0000, v112
	v_fmac_f32_e32 v1, v2, v2
	v_lshlrev_b32_e32 v2, 16, v113
	v_fmac_f32_e32 v1, v2, v2
	v_and_b32_e32 v2, 0xffff0000, v113
	v_fmac_f32_e32 v1, v2, v2
	s_waitcnt vmcnt(9)
; __device__ __forceinline__ float bf2f(unsigned h) { return __uint_as_float(h << 16); }
; template <int DQK, int DV, int MODE, bool QNORM, int SK, int NQ> ...
;     ...
;     for (int qh = 0; qh < NQ; ++qh) {
;         sscale[qh] = 1.0f;
;         if (QNORM) {
;             float ss = 0.f;
; #pragma unroll
;             for (int d0 = 0; d0 < DQK / 16; ++d0)
; #pragma unroll
;                 for (int jq = 0; jq < 8; ++jq) { const float v = bf2f((unsigned)(unsigned short)qf[qh][d0][jq]); ss += v * v; }
;             ss += __shfl_xor(ss, 32);
;             sscale[qh] = qk_scale * __builtin_amdgcn_rsqf(ss * (1.0f / DQK) + EPS);
	v_lshlrev_b32_e32 v2, 16, v102
	v_fmac_f32_e32 v1, v2, v2
	v_and_b32_e32 v2, 0xffff0000, v102
	v_fmac_f32_e32 v1, v2, v2
	v_lshlrev_b32_e32 v2, 16, v103
	v_fmac_f32_e32 v1, v2, v2
	v_and_b32_e32 v2, 0xffff0000, v103
	v_fmac_f32_e32 v1, v2, v2
	v_lshlrev_b32_e32 v2, 16, v104
	v_fmac_f32_e32 v1, v2, v2
	v_and_b32_e32 v2, 0xffff0000, v104
	v_fmac_f32_e32 v1, v2, v2
	v_lshlrev_b32_e32 v2, 16, v105
	v_fmac_f32_e32 v1, v2, v2
	v_and_b32_e32 v2, 0xffff0000, v105
	v_fmac_f32_e32 v1, v2, v2
	s_waitcnt vmcnt(8)
	v_lshlrev_b32_e32 v2, 16, v130
	v_fmac_f32_e32 v1, v2, v2
	v_and_b32_e32 v2, 0xffff0000, v130
	v_fmac_f32_e32 v1, v2, v2
	v_lshlrev_b32_e32 v2, 16, v131
	v_fmac_f32_e32 v1, v2, v2
	v_and_b32_e32 v2, 0xffff0000, v131
	v_fmac_f32_e32 v1, v2, v2
	v_lshlrev_b32_e32 v2, 16, v132
	v_fmac_f32_e32 v1, v2, v2
	v_and_b32_e32 v2, 0xffff0000, v132
	v_fmac_f32_e32 v1, v2, v2
	v_lshlrev_b32_e32 v2, 16, v133
	v_fmac_f32_e32 v1, v2, v2
	v_and_b32_e32 v2, 0xffff0000, v133
	v_fmac_f32_e32 v1, v2, v2
	s_waitcnt vmcnt(7)
	v_lshlrev_b32_e32 v2, 16, v122
	v_fmac_f32_e32 v1, v2, v2
	v_and_b32_e32 v2, 0xffff0000, v122
	v_fmac_f32_e32 v1, v2, v2
	v_lshlrev_b32_e32 v2, 16, v123
	v_fmac_f32_e32 v1, v2, v2
	v_and_b32_e32 v2, 0xffff0000, v123
	v_fmac_f32_e32 v1, v2, v2
	v_lshlrev_b32_e32 v2, 16, v124
	v_fmac_f32_e32 v1, v2, v2
	v_and_b32_e32 v2, 0xffff0000, v124
	v_fmac_f32_e32 v1, v2, v2
	v_lshlrev_b32_e32 v2, 16, v125
	v_fmac_f32_e32 v1, v2, v2
	v_and_b32_e32 v2, 0xffff0000, v125
	v_fmac_f32_e32 v1, v2, v2
	s_waitcnt vmcnt(6)
	v_lshlrev_b32_e32 v2, 16, v114
	v_fmac_f32_e32 v1, v2, v2
	v_and_b32_e32 v2, 0xffff0000, v114
	v_fmac_f32_e32 v1, v2, v2
	v_lshlrev_b32_e32 v2, 16, v115
	v_fmac_f32_e32 v1, v2, v2
	v_and_b32_e32 v2, 0xffff0000, v115
	v_fmac_f32_e32 v1, v2, v2
	v_lshlrev_b32_e32 v2, 16, v116
	v_fmac_f32_e32 v1, v2, v2
	v_and_b32_e32 v2, 0xffff0000, v116
	v_fmac_f32_e32 v1, v2, v2
	v_lshlrev_b32_e32 v2, 16, v117
	v_fmac_f32_e32 v1, v2, v2
	v_and_b32_e32 v2, 0xffff0000, v117
	v_fmac_f32_e32 v1, v2, v2
	s_waitcnt vmcnt(5)
	v_lshlrev_b32_e32 v2, 16, v106
	v_fmac_f32_e32 v1, v2, v2
	v_and_b32_e32 v2, 0xffff0000, v106
	v_fmac_f32_e32 v1, v2, v2
	v_lshlrev_b32_e32 v2, 16, v107
	v_fmac_f32_e32 v1, v2, v2
	v_and_b32_e32 v2, 0xffff0000, v107
	v_fmac_f32_e32 v1, v2, v2
	v_lshlrev_b32_e32 v2, 16, v108
	v_fmac_f32_e32 v1, v2, v2
	v_and_b32_e32 v2, 0xffff0000, v108
	v_fmac_f32_e32 v1, v2, v2
	v_lshlrev_b32_e32 v2, 16, v109
	v_fmac_f32_e32 v1, v2, v2
	v_and_b32_e32 v2, 0xffff0000, v109
	v_fmac_f32_e32 v1, v2, v2
	s_waitcnt vmcnt(4)
	v_lshlrev_b32_e32 v2, 16, v98
	v_fmac_f32_e32 v1, v2, v2
	v_and_b32_e32 v2, 0xffff0000, v98
	v_fmac_f32_e32 v1, v2, v2
	v_lshlrev_b32_e32 v2, 16, v99
	v_fmac_f32_e32 v1, v2, v2
	v_and_b32_e32 v2, 0xffff0000, v99
	v_fmac_f32_e32 v1, v2, v2
	v_lshlrev_b32_e32 v2, 16, v100
	v_fmac_f32_e32 v1, v2, v2
	v_and_b32_e32 v2, 0xffff0000, v100
	v_fmac_f32_e32 v1, v2, v2
	v_lshlrev_b32_e32 v2, 16, v101
	v_fmac_f32_e32 v1, v2, v2
	v_and_b32_e32 v2, 0xffff0000, v101
	v_fmac_f32_e32 v1, v2, v2
	s_waitcnt vmcnt(3)
	v_lshlrev_b32_e32 v2, 16, v94
	v_fmac_f32_e32 v1, v2, v2
	v_and_b32_e32 v2, 0xffff0000, v94
	v_fmac_f32_e32 v1, v2, v2
	v_lshlrev_b32_e32 v2, 16, v95
	v_fmac_f32_e32 v1, v2, v2
	v_and_b32_e32 v2, 0xffff0000, v95
	v_fmac_f32_e32 v1, v2, v2
	v_lshlrev_b32_e32 v2, 16, v96
	v_fmac_f32_e32 v1, v2, v2
	v_and_b32_e32 v2, 0xffff0000, v96
	v_fmac_f32_e32 v1, v2, v2
	v_lshlrev_b32_e32 v2, 16, v97
	v_fmac_f32_e32 v1, v2, v2
	v_and_b32_e32 v2, 0xffff0000, v97
	v_fmac_f32_e32 v1, v2, v2
	s_waitcnt vmcnt(2)
	v_lshlrev_b32_e32 v2, 16, v90
	v_fmac_f32_e32 v1, v2, v2
	v_and_b32_e32 v2, 0xffff0000, v90
	v_fmac_f32_e32 v1, v2, v2
	v_lshlrev_b32_e32 v2, 16, v91
	v_fmac_f32_e32 v1, v2, v2
	v_and_b32_e32 v2, 0xffff0000, v91
	v_fmac_f32_e32 v1, v2, v2
	v_lshlrev_b32_e32 v2, 16, v92
	v_fmac_f32_e32 v1, v2, v2
	v_and_b32_e32 v2, 0xffff0000, v92
	v_fmac_f32_e32 v1, v2, v2
	v_lshlrev_b32_e32 v2, 16, v93
	v_fmac_f32_e32 v1, v2, v2
	v_and_b32_e32 v2, 0xffff0000, v93
	v_fmac_f32_e32 v1, v2, v2
	s_waitcnt vmcnt(1)
	v_lshlrev_b32_e32 v2, 16, v86
	v_fmac_f32_e32 v1, v2, v2
	v_and_b32_e32 v2, 0xffff0000, v86
	v_fmac_f32_e32 v1, v2, v2
	v_lshlrev_b32_e32 v2, 16, v87
	v_fmac_f32_e32 v1, v2, v2
	v_and_b32_e32 v2, 0xffff0000, v87
	v_fmac_f32_e32 v1, v2, v2
	v_lshlrev_b32_e32 v2, 16, v88
	v_fmac_f32_e32 v1, v2, v2
	v_and_b32_e32 v2, 0xffff0000, v88
	v_fmac_f32_e32 v1, v2, v2
	v_lshlrev_b32_e32 v2, 16, v89
	v_fmac_f32_e32 v1, v2, v2
	v_and_b32_e32 v2, 0xffff0000, v89
	v_fmac_f32_e32 v1, v2, v2
	s_waitcnt vmcnt(0)
	v_lshlrev_b32_e32 v2, 16, v82
	v_fmac_f32_e32 v1, v2, v2
	v_and_b32_e32 v2, 0xffff0000, v82
	v_fmac_f32_e32 v1, v2, v2
	v_lshlrev_b32_e32 v2, 16, v83
	v_fmac_f32_e32 v1, v2, v2
	v_and_b32_e32 v2, 0xffff0000, v83
	v_fmac_f32_e32 v1, v2, v2
	v_lshlrev_b32_e32 v2, 16, v84
	v_fmac_f32_e32 v1, v2, v2
	v_and_b32_e32 v2, 0xffff0000, v84
	v_fmac_f32_e32 v1, v2, v2
	v_lshlrev_b32_e32 v2, 16, v85
	v_fmac_f32_e32 v1, v2, v2
	v_and_b32_e32 v2, 0xffff0000, v85
	v_fmac_f32_e32 v1, v2, v2
	ds_bpermute_b32 v14, v222, v1
	s_and_saveexec_b64 s[16:17], s[4:5]
	s_cbranch_execnz .LBB0_4667
	s_or_b64 exec, exec, s[16:17]
	s_and_saveexec_b64 s[16:17], s[6:7]
	s_cbranch_execnz .LBB0_4668
